# v28 + LRU segment scan: all 32 LDS reads of the first per-item scan issued up front (one LDS latency instead of four)
# speedup vs baseline: 1.0023x; 1.0023x over previous
; __device__ __forceinline__ bf16_t f2bf(float f) { return (bf16_t)(cvt_pk_bf16(f, 0.f) & 0xffffu); }
; __device__ __forceinline__ float bf2f(bf16_t b) { return __uint_as_float(((unsigned)b) << 16); }
; __device__ __forceinline__ float sigm(float x) { return __builtin_amdgcn_rcpf(1.0f + __expf(-x)); }
; template <int PASS>
; __device__ void lru_items(const Params& p, unsigned char* shm, int l) {
;     ...
;         { const int j = tid & 63;
; #pragma unroll
;           for (int i = 0; i < 8; ++i) { const int t = (tid >> 6) + 8 * i;
;               const float v = cb + bf2f(xraw[t * 64 + j]) * c0 + bf2f(xraw[(t + 1) * 64 + j]) * c1 + bf2f(xraw[(t + 2) * 64 + j]) * c2 + bf2f(xraw[(t + 3) * 64 + j]) * c3;
;               xcf[t * 65 + j] = v; xcb[t * 72 + j] = f2bf(v); } }
;         __syncthreads();
;         { const int d = w >> 2, tt = w & 3;
;           const bf16x8 a0 = *(const bf16x8*)(xcb + (tt * 16 + fr) * 72 + fq * 8), a1 = *(const bf16x8*)(xcb + (tt * 16 + fr) * 72 + 32 + fq * 8);
; #pragma unroll
;           for (int jt = 0; jt < 4; ++jt) {
;               f32x4 accr = (f32x4){0.f, 0.f, 0.f, 0.f}, acci = (f32x4){0.f, 0.f, 0.f, 0.f};
;               const bf16_t* wr_ = wt + ((d * 2 + 0) * 64 + jt * 16 + fr) * 72 + fq * 8; const bf16_t* wi_ = wt + ((d * 2 + 1) * 64 + jt * 16 + fr) * 72 + fq * 8;
;               accr = __builtin_amdgcn_mfma_f32_16x16x32_bf16(a0, *(const bf16x8*)wr_, accr, 0, 0, 0);
;               accr = __builtin_amdgcn_mfma_f32_16x16x32_bf16(a1, *(const bf16x8*)(wr_ + 32), accr, 0, 0, 0);
;               acci = __builtin_amdgcn_mfma_f32_16x16x32_bf16(a0, *(const bf16x8*)wi_, acci, 0, 0, 0);
;               acci = __builtin_amdgcn_mfma_f32_16x16x32_bf16(a1, *(const bf16x8*)(wi_ + 32), acci, 0, 0, 0);
;               const int j = jt * 16 + fr;
; #pragma unroll
;               for (int i = 0; i < 4; ++i) { const int t = tt * 16 + fq * 4 + i;
;                   const float r = sigm(accr[i] + gba[jt]), ig = sigm(acci[i] + gbx[jt]), a = __expf(r * gsp[jt]);
;                   As[(d * 64 + t) * 64 + j] = a;
;                   Bs[(d * 64 + t) * 64 + j] = sqrtf(fmaxf(1.0f - a * a, 0.f)) * ig * xcf[t * 65 + j]; }
;           } }
.LBB0_214:
	s_mov_b32 s0, 0xf800000
	v_lshrrev_b32_e32 v183, 6, v229
	v_and_b32_e32 v184, 63, v229
	v_lshlrev_b32_e32 v185, 10, v183
	v_lshl_add_u32 v185, v184, 1, v185
	ds_read_u16 v186, v185
	ds_read_u16 v187, v185 offset:128
	ds_read_u16 v188, v185 offset:256
	ds_read_u16 v189, v185 offset:384
	ds_read_u16 v190, v185 offset:512
	ds_read_u16 v191, v185 offset:640
	ds_read_u16 v192, v185 offset:768
	ds_read_u16 v193, v185 offset:896
	ds_read_u16 v194, v185 offset:1024
	ds_read_u16 v196, v185 offset:1152
	ds_read_u16 v197, v185 offset:1280
	v_mul_u32_u24_e32 v206, 0x820, v183
	v_lshl_add_u32 v206, v184, 2, v206
	v_mul_u32_u24_e32 v207, 0x480, v183
	v_lshl_add_u32 v207, v184, 1, v207
	s_waitcnt lgkmcnt(0)
	v_lshlrev_b32_e32 v186, 16, v186
	v_lshlrev_b32_e32 v187, 16, v187
	v_lshlrev_b32_e32 v188, 16, v188
	v_lshlrev_b32_e32 v189, 16, v189
	v_lshlrev_b32_e32 v190, 16, v190
	v_lshlrev_b32_e32 v191, 16, v191
	v_lshlrev_b32_e32 v192, 16, v192
	v_lshlrev_b32_e32 v193, 16, v193
	v_lshlrev_b32_e32 v194, 16, v194
	v_lshlrev_b32_e32 v196, 16, v196
	v_lshlrev_b32_e32 v197, 16, v197
	v_fma_f32 v198, v151, v186, v150
	v_fma_f32 v199, v151, v187, v150
	v_fma_f32 v200, v151, v188, v150
	v_fma_f32 v201, v151, v189, v150
	v_fma_f32 v202, v151, v190, v150
	v_fma_f32 v203, v151, v191, v150
	v_fma_f32 v204, v151, v192, v150
	v_fma_f32 v205, v151, v193, v150
	v_fmac_f32_e32 v198, v154, v187
	v_fmac_f32_e32 v199, v154, v188
	v_fmac_f32_e32 v200, v154, v189
	v_fmac_f32_e32 v201, v154, v190
	v_fmac_f32_e32 v202, v154, v191
	v_fmac_f32_e32 v203, v154, v192
	v_fmac_f32_e32 v204, v154, v193
	v_fmac_f32_e32 v205, v154, v194
	v_fmac_f32_e32 v198, v153, v188
	v_fmac_f32_e32 v199, v153, v189
	v_fmac_f32_e32 v200, v153, v190
	v_fmac_f32_e32 v201, v153, v191
	v_fmac_f32_e32 v202, v153, v192
	v_fmac_f32_e32 v203, v153, v193
	v_fmac_f32_e32 v204, v153, v194
	v_fmac_f32_e32 v205, v153, v196
	v_fmac_f32_e32 v198, v152, v189
	v_fmac_f32_e32 v199, v152, v190
	v_fmac_f32_e32 v200, v152, v191
	v_fmac_f32_e32 v201, v152, v192
	v_fmac_f32_e32 v202, v152, v193
	v_fmac_f32_e32 v203, v152, v194
	v_fmac_f32_e32 v204, v152, v196
	v_fmac_f32_e32 v205, v152, v197
	ds_write_b32 v206, v198 offset:8704
	ds_write_b32 v206, v199 offset:8964
	ds_write_b32 v206, v200 offset:9224
	ds_write_b32 v206, v201 offset:9484
	ds_write_b32 v206, v202 offset:9744
	ds_write_b32 v206, v203 offset:10004
	ds_write_b32 v206, v204 offset:10264
	ds_write_b32 v206, v205 offset:10524
	v_cvt_pk_bf16_f32 v186, v198, v1
	v_cvt_pk_bf16_f32 v187, v199, v1
	ds_write_b16 v207, v186 offset:25344
	v_cvt_pk_bf16_f32 v188, v200, v1
	ds_write_b16 v207, v187 offset:25488
	v_cvt_pk_bf16_f32 v189, v201, v1
	ds_write_b16 v207, v188 offset:25632
	v_cvt_pk_bf16_f32 v190, v202, v1
	ds_write_b16 v207, v189 offset:25776
	v_cvt_pk_bf16_f32 v191, v203, v1
	ds_write_b16 v207, v190 offset:25920
	v_cvt_pk_bf16_f32 v192, v204, v1
	ds_write_b16 v207, v191 offset:26064
	v_cvt_pk_bf16_f32 v193, v205, v1
	ds_write_b16 v207, v192 offset:26208
	ds_write_b16 v207, v193 offset:26352
	s_waitcnt lgkmcnt(0)
	s_barrier
	ds_read_b32 v186, v149 offset:8704
	ds_read_b32 v187, v149 offset:8964
	ds_read_b32 v188, v149 offset:9224
	ds_read_b32 v189, v149 offset:9484
	ds_read_b32 v190, v149 offset:8768
	ds_read_b32 v191, v149 offset:9028
	ds_read_b32 v192, v149 offset:9288
	ds_read_b32 v193, v149 offset:9548
	ds_read_b32 v194, v149 offset:8832
	ds_read_b32 v196, v149 offset:9092
	ds_read_b32 v197, v149 offset:9352
	ds_read_b32 v198, v149 offset:9612
	ds_read_b32 v199, v149 offset:8896
	ds_read_b32 v200, v149 offset:9156
	ds_read_b32 v201, v149 offset:9416
	ds_read_b32 v202, v149 offset:9676
	ds_read_b128 v[18:21], v47 offset:25344
	ds_read_b128 v[14:17], v47 offset:25408
	ds_read_b128 v[160:163], v72 offset:34560
	ds_read_b128 v[164:167], v72 offset:34624
	s_waitcnt lgkmcnt(1)
	v_mfma_f32_16x16x32_bf16 v[160:163], v[18:21], v[160:163], 0
	ds_read_b128 v[168:171], v73 offset:43840
	s_waitcnt lgkmcnt(1)
	v_mfma_f32_16x16x32_bf16 v[160:163], v[14:17], v[164:167], v[160:163]
	ds_read_b128 v[164:167], v73 offset:43776
	s_waitcnt lgkmcnt(0)
	v_mfma_f32_16x16x32_bf16 v[164:167], v[18:21], v[164:167], 0
	s_waitcnt vmcnt(9)
	s_nop 3
	v_fmamk_f32 v0, v160, 0xbfb8aa3b, v157
	v_exp_f32_e32 v0, v0
	v_mfma_f32_16x16x32_bf16 v[164:167], v[14:17], v[168:171], v[164:167]
	v_add_f32_e32 v0, 1.0, v0
	v_rcp_f32_e32 v0, v0
	s_nop 0
	v_mul_f32_e32 v0, v23, v0
	v_exp_f32_e32 v0, v0
	s_waitcnt vmcnt(5)
	s_nop 1
	v_fmamk_f32 v35, v164, 0xbfb8aa3b, v155
	v_exp_f32_e32 v35, v35
	v_fma_f32 v36, -v0, v0, 1.0
	v_max_f32_e32 v36, 0, v36
	ds_write_b32 v74, v0
	v_add_f32_e32 v35, 1.0, v35
	v_sqrt_f32_e32 v37, v36
	v_rcp_f32_e32 v35, v35
	v_mov_b32_e32 v0, v37
	v_fmamk_f32 v37, v161, 0xbfb8aa3b, v157
	v_exp_f32_e32 v37, v37
	s_nop 0
	v_add_f32_e32 v36, 1.0, v37
	v_rcp_f32_e32 v36, v36
	v_mul_f32_e32 v0, v35, v0
	s_waitcnt lgkmcnt(0)
	v_mul_f32_e32 v0, v186, v0
	ds_write_b32 v75, v0
	v_mul_f32_e32 v0, v23, v36
	v_exp_f32_e32 v0, v0
	v_fmamk_f32 v35, v165, 0xbfb8aa3b, v155
	v_exp_f32_e32 v35, v35
	v_fma_f32 v36, -v0, v0, 1.0
	v_max_f32_e32 v36, 0, v36
	ds_write_b32 v76, v0
	v_add_f32_e32 v35, 1.0, v35
	v_sqrt_f32_e32 v37, v36
	v_rcp_f32_e32 v35, v35
	v_mov_b32_e32 v0, v37
	v_fmamk_f32 v37, v162, 0xbfb8aa3b, v157
	v_exp_f32_e32 v37, v37
	s_nop 0
	v_add_f32_e32 v36, 1.0, v37
	v_rcp_f32_e32 v36, v36
	v_mul_f32_e32 v0, v35, v0
	v_mul_f32_e32 v0, v187, v0
	ds_write_b32 v77, v0
	v_mul_f32_e32 v0, v23, v36
	v_exp_f32_e32 v0, v0
	v_fmamk_f32 v35, v166, 0xbfb8aa3b, v155
	v_exp_f32_e32 v35, v35
	v_fma_f32 v36, -v0, v0, 1.0
	v_max_f32_e32 v36, 0, v36
	ds_write_b32 v78, v0
	v_add_f32_e32 v35, 1.0, v35
	v_sqrt_f32_e32 v37, v36
	v_rcp_f32_e32 v35, v35
	v_mov_b32_e32 v0, v37
	v_fmamk_f32 v37, v163, 0xbfb8aa3b, v157
	v_exp_f32_e32 v37, v37
	s_nop 0
	v_add_f32_e32 v36, 1.0, v37
	v_rcp_f32_e32 v36, v36
	v_mul_f32_e32 v0, v35, v0
	v_mul_f32_e32 v0, v188, v0
	ds_write_b32 v79, v0
	v_mul_f32_e32 v0, v23, v36
	v_exp_f32_e32 v0, v0
	v_fmamk_f32 v35, v167, 0xbfb8aa3b, v155
	v_exp_f32_e32 v35, v35
	v_fma_f32 v36, -v0, v0, 1.0
	v_max_f32_e32 v36, 0, v36
	ds_write_b32 v80, v0
	v_add_f32_e32 v35, 1.0, v35
	v_sqrt_f32_e32 v37, v36
	v_rcp_f32_e32 v35, v35
	v_mov_b32_e32 v0, v37
	v_mul_f32_e32 v0, v35, v0
	v_mul_f32_e32 v0, v0, v189
	ds_write_b32 v81, v0
	ds_read_b128 v[160:163], v72 offset:36864
	ds_read_b128 v[164:167], v72 offset:36928
	s_waitcnt lgkmcnt(1)
; __device__ __forceinline__ float sigm(float x) { return __builtin_amdgcn_rcpf(1.0f + __expf(-x)); }
; template <int PASS>
; __device__ void lru_items(const Params& p, unsigned char* shm, int l) {
;     ...
;           for (int jt = 0; jt < 4; ++jt) {
;               f32x4 accr = (f32x4){0.f, 0.f, 0.f, 0.f}, acci = (f32x4){0.f, 0.f, 0.f, 0.f};
;               const bf16_t* wr_ = wt + ((d * 2 + 0) * 64 + jt * 16 + fr) * 72 + fq * 8; const bf16_t* wi_ = wt + ((d * 2 + 1) * 64 + jt * 16 + fr) * 72 + fq * 8;
;               accr = __builtin_amdgcn_mfma_f32_16x16x32_bf16(a0, *(const bf16x8*)wr_, accr, 0, 0, 0);
;               accr = __builtin_amdgcn_mfma_f32_16x16x32_bf16(a1, *(const bf16x8*)(wr_ + 32), accr, 0, 0, 0);
;               acci = __builtin_amdgcn_mfma_f32_16x16x32_bf16(a0, *(const bf16x8*)wi_, acci, 0, 0, 0);
;               acci = __builtin_amdgcn_mfma_f32_16x16x32_bf16(a1, *(const bf16x8*)(wi_ + 32), acci, 0, 0, 0);
;               const int j = jt * 16 + fr;
; #pragma unroll
;               for (int i = 0; i < 4; ++i) { const int t = tt * 16 + fq * 4 + i;
;                   const float r = sigm(accr[i] + gba[jt]), ig = sigm(acci[i] + gbx[jt]), a = __expf(r * gsp[jt]);
;                   As[(d * 64 + t) * 64 + j] = a;
;                   Bs[(d * 64 + t) * 64 + j] = sqrtf(fmaxf(1.0f - a * a, 0.f)) * ig * xcf[t * 65 + j]; }
;           } }
	v_mfma_f32_16x16x32_bf16 v[160:163], v[18:21], v[160:163], 0
	ds_read_b128 v[168:171], v73 offset:46144
	s_waitcnt lgkmcnt(1)
	v_mfma_f32_16x16x32_bf16 v[160:163], v[14:17], v[164:167], v[160:163]
	ds_read_b128 v[164:167], v73 offset:46080
	s_waitcnt lgkmcnt(0)
	v_mfma_f32_16x16x32_bf16 v[164:167], v[18:21], v[164:167], 0
	s_nop 4
	v_fmamk_f32 v0, v160, 0xbfb8aa3b, v158
	v_exp_f32_e32 v0, v0
	v_mfma_f32_16x16x32_bf16 v[164:167], v[14:17], v[168:171], v[164:167]
	v_add_f32_e32 v0, 1.0, v0
	v_rcp_f32_e32 v0, v0
	s_nop 0
	v_mul_f32_e32 v0, v22, v0
	v_exp_f32_e32 v0, v0
	s_waitcnt vmcnt(4)
	s_nop 1
	v_fmamk_f32 v35, v164, 0xbfb8aa3b, v156
	v_exp_f32_e32 v35, v35
	v_fma_f32 v36, -v0, v0, 1.0
	v_max_f32_e32 v36, 0, v36
	ds_write_b32 v82, v0
	v_add_f32_e32 v35, 1.0, v35
	v_sqrt_f32_e32 v37, v36
	v_rcp_f32_e32 v35, v35
	v_mov_b32_e32 v0, v37
	v_fmamk_f32 v37, v161, 0xbfb8aa3b, v158
	v_exp_f32_e32 v37, v37
	s_nop 0
	v_add_f32_e32 v36, 1.0, v37
	v_rcp_f32_e32 v36, v36
	v_mul_f32_e32 v0, v35, v0
	v_mul_f32_e32 v0, v190, v0
	ds_write_b32 v83, v0
	v_mul_f32_e32 v0, v22, v36
	v_exp_f32_e32 v0, v0
	v_fmamk_f32 v35, v165, 0xbfb8aa3b, v156
	v_exp_f32_e32 v35, v35
	v_fma_f32 v36, -v0, v0, 1.0
	v_max_f32_e32 v36, 0, v36
	ds_write_b32 v84, v0
	v_add_f32_e32 v35, 1.0, v35
	v_sqrt_f32_e32 v37, v36
	v_rcp_f32_e32 v35, v35
	v_mov_b32_e32 v0, v37
	v_fmamk_f32 v37, v162, 0xbfb8aa3b, v158
	v_exp_f32_e32 v37, v37
	s_nop 0
	v_add_f32_e32 v36, 1.0, v37
	v_rcp_f32_e32 v36, v36
	v_mul_f32_e32 v0, v35, v0
	v_mul_f32_e32 v0, v191, v0
	ds_write_b32 v85, v0
	v_mul_f32_e32 v0, v22, v36
	v_exp_f32_e32 v0, v0
	v_fmamk_f32 v35, v166, 0xbfb8aa3b, v156
	v_exp_f32_e32 v35, v35
	v_fma_f32 v36, -v0, v0, 1.0
	v_max_f32_e32 v36, 0, v36
	ds_write_b32 v86, v0
	v_add_f32_e32 v35, 1.0, v35
	v_sqrt_f32_e32 v37, v36
	v_rcp_f32_e32 v35, v35
	v_mov_b32_e32 v0, v37
	v_fmamk_f32 v37, v163, 0xbfb8aa3b, v158
	v_exp_f32_e32 v37, v37
	s_nop 0
	v_add_f32_e32 v36, 1.0, v37
	v_rcp_f32_e32 v36, v36
	v_mul_f32_e32 v0, v35, v0
	v_mul_f32_e32 v0, v192, v0
	ds_write_b32 v87, v0
	v_mul_f32_e32 v0, v22, v36
	v_exp_f32_e32 v0, v0
	v_fmamk_f32 v35, v167, 0xbfb8aa3b, v156
	v_exp_f32_e32 v35, v35
	v_fma_f32 v36, -v0, v0, 1.0
	v_max_f32_e32 v36, 0, v36
	ds_write_b32 v88, v0
	v_add_f32_e32 v35, 1.0, v35
	v_sqrt_f32_e32 v37, v36
	v_rcp_f32_e32 v35, v35
	v_mov_b32_e32 v0, v37
	v_mul_f32_e32 v0, v35, v0
	v_mul_f32_e32 v0, v0, v193
	ds_write_b32 v89, v0
	ds_read_b128 v[160:163], v72 offset:39168
	ds_read_b128 v[164:167], v72 offset:39232
	s_waitcnt lgkmcnt(1)
	v_mfma_f32_16x16x32_bf16 v[160:163], v[18:21], v[160:163], 0
	ds_read_b128 v[168:171], v73 offset:48448
	s_waitcnt lgkmcnt(1)
	v_mfma_f32_16x16x32_bf16 v[160:163], v[14:17], v[164:167], v[160:163]
	ds_read_b128 v[164:167], v73 offset:48384
	s_waitcnt lgkmcnt(0)
	v_mfma_f32_16x16x32_bf16 v[164:167], v[18:21], v[164:167], 0
	s_nop 4
	v_fmamk_f32 v0, v160, 0xbfb8aa3b, v40
	v_exp_f32_e32 v0, v0
	v_mfma_f32_16x16x32_bf16 v[164:167], v[14:17], v[168:171], v[164:167]
	v_add_f32_e32 v0, 1.0, v0
	v_rcp_f32_e32 v0, v0
	s_nop 0
	v_mul_f32_e32 v0, v25, v0
	v_exp_f32_e32 v0, v0
	s_waitcnt vmcnt(3)
	s_nop 1
	v_fmamk_f32 v35, v164, 0xbfb8aa3b, v38
	v_exp_f32_e32 v35, v35
	v_fma_f32 v36, -v0, v0, 1.0
	v_max_f32_e32 v36, 0, v36
	ds_write_b32 v90, v0
	v_add_f32_e32 v35, 1.0, v35
	v_sqrt_f32_e32 v37, v36
	v_rcp_f32_e32 v35, v35
	v_mov_b32_e32 v0, v37
	v_fmamk_f32 v37, v161, 0xbfb8aa3b, v40
	v_exp_f32_e32 v37, v37
	s_nop 0
	v_add_f32_e32 v36, 1.0, v37
	v_rcp_f32_e32 v36, v36
	v_mul_f32_e32 v0, v35, v0
	v_mul_f32_e32 v0, v194, v0
	ds_write_b32 v91, v0
	v_mul_f32_e32 v0, v25, v36
	v_exp_f32_e32 v0, v0
	v_fmamk_f32 v35, v165, 0xbfb8aa3b, v38
	v_exp_f32_e32 v35, v35
	v_fma_f32 v36, -v0, v0, 1.0
	v_max_f32_e32 v36, 0, v36
	ds_write_b32 v92, v0
	v_add_f32_e32 v35, 1.0, v35
	v_sqrt_f32_e32 v37, v36
	v_rcp_f32_e32 v35, v35
	v_mov_b32_e32 v0, v37
	v_fmamk_f32 v37, v162, 0xbfb8aa3b, v40
	v_exp_f32_e32 v37, v37
	s_nop 0
	v_add_f32_e32 v36, 1.0, v37
	v_rcp_f32_e32 v36, v36
	v_mul_f32_e32 v0, v35, v0
	v_mul_f32_e32 v0, v196, v0
	ds_write_b32 v93, v0
	v_mul_f32_e32 v0, v25, v36
	v_exp_f32_e32 v0, v0
	v_fmamk_f32 v35, v166, 0xbfb8aa3b, v38
	v_exp_f32_e32 v35, v35
	v_fma_f32 v36, -v0, v0, 1.0
	v_max_f32_e32 v36, 0, v36
	ds_write_b32 v94, v0
	v_add_f32_e32 v35, 1.0, v35
	v_sqrt_f32_e32 v37, v36
	v_rcp_f32_e32 v35, v35
	v_mov_b32_e32 v0, v37
	v_fmamk_f32 v37, v163, 0xbfb8aa3b, v40
	v_exp_f32_e32 v37, v37
	s_nop 0
	v_add_f32_e32 v36, 1.0, v37
	v_rcp_f32_e32 v36, v36
	v_mul_f32_e32 v0, v35, v0
	v_mul_f32_e32 v0, v197, v0
	ds_write_b32 v95, v0
	v_mul_f32_e32 v0, v25, v36
	v_exp_f32_e32 v0, v0
	v_fmamk_f32 v35, v167, 0xbfb8aa3b, v38
	v_exp_f32_e32 v35, v35
	v_fma_f32 v36, -v0, v0, 1.0
	v_max_f32_e32 v36, 0, v36
	ds_write_b32 v96, v0
	v_add_f32_e32 v35, 1.0, v35
	v_sqrt_f32_e32 v37, v36
	v_rcp_f32_e32 v35, v35
	v_mov_b32_e32 v0, v37
	v_mul_f32_e32 v0, v35, v0
	v_mul_f32_e32 v0, v0, v198
	ds_write_b32 v97, v0
	ds_read_b128 v[160:163], v72 offset:41472
	ds_read_b128 v[164:167], v72 offset:41536
	s_waitcnt lgkmcnt(1)
; __device__ __forceinline__ float sigm(float x) { return __builtin_amdgcn_rcpf(1.0f + __expf(-x)); }
; template <int PASS>
; __device__ void lru_items(const Params& p, unsigned char* shm, int l) {
;     ...
;           for (int jt = 0; jt < 4; ++jt) {
;               f32x4 accr = (f32x4){0.f, 0.f, 0.f, 0.f}, acci = (f32x4){0.f, 0.f, 0.f, 0.f};
;               const bf16_t* wr_ = wt + ((d * 2 + 0) * 64 + jt * 16 + fr) * 72 + fq * 8; const bf16_t* wi_ = wt + ((d * 2 + 1) * 64 + jt * 16 + fr) * 72 + fq * 8;
;               accr = __builtin_amdgcn_mfma_f32_16x16x32_bf16(a0, *(const bf16x8*)wr_, accr, 0, 0, 0);
;               accr = __builtin_amdgcn_mfma_f32_16x16x32_bf16(a1, *(const bf16x8*)(wr_ + 32), accr, 0, 0, 0);
;               acci = __builtin_amdgcn_mfma_f32_16x16x32_bf16(a0, *(const bf16x8*)wi_, acci, 0, 0, 0);
;               acci = __builtin_amdgcn_mfma_f32_16x16x32_bf16(a1, *(const bf16x8*)(wi_ + 32), acci, 0, 0, 0);
;               const int j = jt * 16 + fr;
; #pragma unroll
;               for (int i = 0; i < 4; ++i) { const int t = tt * 16 + fq * 4 + i;
;                   const float r = sigm(accr[i] + gba[jt]), ig = sigm(acci[i] + gbx[jt]), a = __expf(r * gsp[jt]);
;                   As[(d * 64 + t) * 64 + j] = a;
;                   Bs[(d * 64 + t) * 64 + j] = sqrtf(fmaxf(1.0f - a * a, 0.f)) * ig * xcf[t * 65 + j]; }
;           } }
;         __syncthreads();
;         {
;             const int seg = tid >> 7, d = (tid >> 6) & 1, j = tid & 63;
;             float h = 0.f, P = 1.f;
; #pragma unroll
;             for (int s = 0; s < 16; ++s) { const int st = seg * 16 + s, t = d ? 63 - st : st; const float a = As[(d * 64 + t) * 64 + j]; h = a * h + Bs[(d * 64 + t) * 64 + j]; P *= a; }
;             Pq[seg * 128 + (tid & 127)] = P; Hq[seg * 128 + (tid & 127)] = h;
	v_mfma_f32_16x16x32_bf16 v[160:163], v[18:21], v[160:163], 0
	ds_read_b128 v[168:171], v73 offset:50752
	s_waitcnt lgkmcnt(1)
	v_mfma_f32_16x16x32_bf16 v[160:163], v[14:17], v[164:167], v[160:163]
	ds_read_b128 v[164:167], v73 offset:50688
	s_waitcnt lgkmcnt(0)
	v_mfma_f32_16x16x32_bf16 v[18:21], v[18:21], v[164:167], 0
	s_nop 4
	v_fmamk_f32 v0, v160, 0xbfb8aa3b, v41
	v_exp_f32_e32 v0, v0
	s_nop 0
	v_mfma_f32_16x16x32_bf16 v[14:17], v[14:17], v[168:171], v[18:21]
	v_add_f32_e32 v0, 1.0, v0
	v_rcp_f32_e32 v0, v0
	s_nop 0
	v_mul_f32_e32 v0, v24, v0
	v_exp_f32_e32 v0, v0
	s_waitcnt vmcnt(2)
	s_nop 1
	v_fmamk_f32 v14, v14, 0xbfb8aa3b, v39
	v_exp_f32_e32 v14, v14
	v_fma_f32 v18, -v0, v0, 1.0
	v_max_f32_e32 v18, 0, v18
	ds_write_b32 v98, v0
	v_add_f32_e32 v14, 1.0, v14
	v_sqrt_f32_e32 v19, v18
	v_rcp_f32_e32 v14, v14
	v_mov_b32_e32 v0, v19
	v_fmamk_f32 v19, v161, 0xbfb8aa3b, v41
	v_exp_f32_e32 v19, v19
	s_nop 0
	v_add_f32_e32 v18, 1.0, v19
	v_rcp_f32_e32 v18, v18
	v_mul_f32_e32 v0, v14, v0
	v_mul_f32_e32 v0, v199, v0
	ds_write_b32 v99, v0
	v_mul_f32_e32 v0, v24, v18
	v_exp_f32_e32 v0, v0
	v_fmamk_f32 v14, v15, 0xbfb8aa3b, v39
	v_exp_f32_e32 v14, v14
	v_fma_f32 v15, -v0, v0, 1.0
	v_max_f32_e32 v15, 0, v15
	ds_write_b32 v100, v0
	v_add_f32_e32 v14, 1.0, v14
	v_sqrt_f32_e32 v18, v15
	v_rcp_f32_e32 v14, v14
	v_mov_b32_e32 v0, v18
	v_fmamk_f32 v18, v162, 0xbfb8aa3b, v41
	v_exp_f32_e32 v18, v18
	s_nop 0
	v_add_f32_e32 v15, 1.0, v18
	v_rcp_f32_e32 v15, v15
	v_mul_f32_e32 v0, v14, v0
	v_mul_f32_e32 v0, v200, v0
	ds_write_b32 v101, v0
	v_mul_f32_e32 v0, v24, v15
	v_exp_f32_e32 v0, v0
	v_fmamk_f32 v14, v16, 0xbfb8aa3b, v39
	v_exp_f32_e32 v14, v14
	v_fma_f32 v15, -v0, v0, 1.0
	v_max_f32_e32 v15, 0, v15
	ds_write_b32 v102, v0
	v_add_f32_e32 v14, 1.0, v14
	v_sqrt_f32_e32 v16, v15
	v_rcp_f32_e32 v14, v14
	v_mov_b32_e32 v0, v16
	v_fmamk_f32 v16, v163, 0xbfb8aa3b, v41
	v_exp_f32_e32 v16, v16
	s_nop 0
	v_add_f32_e32 v15, 1.0, v16
	v_rcp_f32_e32 v15, v15
	v_mul_f32_e32 v0, v14, v0
	v_mul_f32_e32 v0, v201, v0
	ds_write_b32 v103, v0
	v_mul_f32_e32 v0, v24, v15
	v_exp_f32_e32 v0, v0
	v_fmamk_f32 v14, v17, 0xbfb8aa3b, v39
	v_exp_f32_e32 v14, v14
	v_fma_f32 v15, -v0, v0, 1.0
	v_max_f32_e32 v15, 0, v15
	ds_write_b32 v104, v0
	v_add_f32_e32 v14, 1.0, v14
	v_sqrt_f32_e32 v16, v15
	v_rcp_f32_e32 v14, v14
	v_mov_b32_e32 v0, v16
	v_mul_f32_e32 v0, v14, v0
	v_mul_f32_e32 v0, v0, v202
	ds_write_b32 v105, v0
	s_waitcnt lgkmcnt(0)
	s_barrier
	ds_read_b32 v183, v51
	ds_read_b32 v184, v106
	ds_read_b32 v185, v107
	ds_read_b32 v186, v108
	ds_read_b32 v187, v109
	ds_read_b32 v188, v110
	ds_read_b32 v189, v111
	ds_read_b32 v190, v112
	ds_read_b32 v191, v113
	ds_read_b32 v192, v114
	ds_read_b32 v193, v115
	ds_read_b32 v194, v116
	ds_read_b32 v196, v117
	ds_read_b32 v197, v118
	ds_read_b32 v198, v119
	ds_read_b32 v199, v120
	ds_read_b32 v200, v121
	ds_read_b32 v201, v122
	ds_read_b32 v202, v123
	ds_read_b32 v203, v124
	ds_read_b32 v204, v125
	ds_read_b32 v205, v126
	ds_read_b32 v206, v127
	ds_read_b32 v207, v128
	ds_read_b32 v208, v129
	ds_read_b32 v209, v130
	ds_read_b32 v210, v131
	ds_read_b32 v211, v132
	ds_read_b32 v212, v133
	ds_read_b32 v213, v134
	ds_read_b32 v214, v135
	ds_read_b32 v215, v136
	s_waitcnt lgkmcnt(0)
	v_fmac_f32_e32 v184, 0, v183
	v_fmac_f32_e32 v186, v184, v185
	v_mul_f32_e32 v183, v183, v185
	v_fmac_f32_e32 v188, v186, v187
	v_mul_f32_e32 v183, v183, v187
	v_fmac_f32_e32 v190, v188, v189
	v_mul_f32_e32 v183, v183, v189
	v_fmac_f32_e32 v192, v190, v191
	v_mul_f32_e32 v183, v183, v191
	v_fmac_f32_e32 v194, v192, v193
	v_mul_f32_e32 v183, v183, v193
	v_fmac_f32_e32 v197, v194, v196
	v_mul_f32_e32 v183, v183, v196
	v_fmac_f32_e32 v199, v197, v198
	v_mul_f32_e32 v183, v183, v198
	v_fmac_f32_e32 v201, v199, v200
	v_mul_f32_e32 v183, v183, v200
	v_fmac_f32_e32 v203, v201, v202
	v_mul_f32_e32 v183, v183, v202
	v_fmac_f32_e32 v205, v203, v204
	v_mul_f32_e32 v183, v183, v204
	v_fmac_f32_e32 v207, v205, v206
	v_mul_f32_e32 v183, v183, v206
	v_mul_f32_e32 v183, v183, v208
	v_fmac_f32_e32 v209, v207, v208
	v_mul_f32_e32 v183, v183, v210
	v_fmac_f32_e32 v211, v209, v210
	v_mul_f32_e32 v183, v183, v212
	v_fmac_f32_e32 v213, v211, v212
	v_mul_f32_e32 v183, v183, v214
	v_fmac_f32_e32 v215, v213, v214
	ds_write_b32 v48, v183
	ds_write_b32 v49, v215
	s_waitcnt lgkmcnt(0)
	s_barrier
	s_and_saveexec_b64 s[0:1], s[38:39]
	s_cbranch_execnz .LBB0_217
	s_or_b64 exec, exec, s[0:1]
	s_and_saveexec_b64 s[0:1], s[40:41]
	s_cbranch_execnz .LBB0_218

; __device__ __forceinline__ bf16_t f2bf(float f) { return (bf16_t)(cvt_pk_bf16(f, 0.f) & 0xffffu); }
; __device__ __forceinline__ float bf2f(bf16_t b) { return __uint_as_float(((unsigned)b) << 16); }
; __device__ __forceinline__ float sigm(float x) { return __builtin_amdgcn_rcpf(1.0f + __expf(-x)); }
; template <int PASS>
; __device__ void lru_items(const Params& p, unsigned char* shm, int l) {
;     ...
;         { const int j = tid & 63;
; #pragma unroll
;           for (int i = 0; i < 8; ++i) { const int t = (tid >> 6) + 8 * i;
;               const float v = cb + bf2f(xraw[t * 64 + j]) * c0 + bf2f(xraw[(t + 1) * 64 + j]) * c1 + bf2f(xraw[(t + 2) * 64 + j]) * c2 + bf2f(xraw[(t + 3) * 64 + j]) * c3;
;               xcf[t * 65 + j] = v; xcb[t * 72 + j] = f2bf(v); } }
;         __syncthreads();
;         { const int d = w >> 2, tt = w & 3;
;           const bf16x8 a0 = *(const bf16x8*)(xcb + (tt * 16 + fr) * 72 + fq * 8), a1 = *(const bf16x8*)(xcb + (tt * 16 + fr) * 72 + 32 + fq * 8);
; #pragma unroll
;           for (int jt = 0; jt < 4; ++jt) {
;               f32x4 accr = (f32x4){0.f, 0.f, 0.f, 0.f}, acci = (f32x4){0.f, 0.f, 0.f, 0.f};
;               const bf16_t* wr_ = wt + ((d * 2 + 0) * 64 + jt * 16 + fr) * 72 + fq * 8; const bf16_t* wi_ = wt + ((d * 2 + 1) * 64 + jt * 16 + fr) * 72 + fq * 8;
;               accr = __builtin_amdgcn_mfma_f32_16x16x32_bf16(a0, *(const bf16x8*)wr_, accr, 0, 0, 0);
;               accr = __builtin_amdgcn_mfma_f32_16x16x32_bf16(a1, *(const bf16x8*)(wr_ + 32), accr, 0, 0, 0);
;               acci = __builtin_amdgcn_mfma_f32_16x16x32_bf16(a0, *(const bf16x8*)wi_, acci, 0, 0, 0);
;               acci = __builtin_amdgcn_mfma_f32_16x16x32_bf16(a1, *(const bf16x8*)(wi_ + 32), acci, 0, 0, 0);
;               const int j = jt * 16 + fr;
; #pragma unroll
;               for (int i = 0; i < 4; ++i) { const int t = tt * 16 + fq * 4 + i;
;                   const float r = sigm(accr[i] + gba[jt]), ig = sigm(acci[i] + gbx[jt]), a = __expf(r * gsp[jt]);
;                   As[(d * 64 + t) * 64 + j] = a;
;                   Bs[(d * 64 + t) * 64 + j] = sqrtf(fmaxf(1.0f - a * a, 0.f)) * ig * xcf[t * 65 + j]; }
;           } }
.LBB0_310:
	s_mov_b32 s0, 0xf800000
	v_lshrrev_b32_e32 v183, 6, v229
	v_and_b32_e32 v184, 63, v229
	v_lshlrev_b32_e32 v185, 10, v183
	v_lshl_add_u32 v185, v184, 1, v185
	ds_read_u16 v186, v185
	ds_read_u16 v187, v185 offset:128
	ds_read_u16 v188, v185 offset:256
	ds_read_u16 v189, v185 offset:384
	ds_read_u16 v190, v185 offset:512
	ds_read_u16 v191, v185 offset:640
	ds_read_u16 v192, v185 offset:768
	ds_read_u16 v193, v185 offset:896
	ds_read_u16 v194, v185 offset:1024
	ds_read_u16 v196, v185 offset:1152
	ds_read_u16 v197, v185 offset:1280
	v_mul_u32_u24_e32 v206, 0x820, v183
	v_lshl_add_u32 v206, v184, 2, v206
	v_mul_u32_u24_e32 v207, 0x480, v183
	v_lshl_add_u32 v207, v184, 1, v207
	s_waitcnt lgkmcnt(0)
	v_lshlrev_b32_e32 v186, 16, v186
	v_lshlrev_b32_e32 v187, 16, v187
	v_lshlrev_b32_e32 v188, 16, v188
	v_lshlrev_b32_e32 v189, 16, v189
	v_lshlrev_b32_e32 v190, 16, v190
	v_lshlrev_b32_e32 v191, 16, v191
	v_lshlrev_b32_e32 v192, 16, v192
	v_lshlrev_b32_e32 v193, 16, v193
	v_lshlrev_b32_e32 v194, 16, v194
	v_lshlrev_b32_e32 v196, 16, v196
	v_lshlrev_b32_e32 v197, 16, v197
	v_fma_f32 v198, v149, v186, v148
	v_fma_f32 v199, v149, v187, v148
	v_fma_f32 v200, v149, v188, v148
	v_fma_f32 v201, v149, v189, v148
	v_fma_f32 v202, v149, v190, v148
	v_fma_f32 v203, v149, v191, v148
	v_fma_f32 v204, v149, v192, v148
	v_fma_f32 v205, v149, v193, v148
	v_fmac_f32_e32 v198, v152, v187
	v_fmac_f32_e32 v199, v152, v188
	v_fmac_f32_e32 v200, v152, v189
	v_fmac_f32_e32 v201, v152, v190
	v_fmac_f32_e32 v202, v152, v191
	v_fmac_f32_e32 v203, v152, v192
	v_fmac_f32_e32 v204, v152, v193
	v_fmac_f32_e32 v205, v152, v194
	v_fmac_f32_e32 v198, v151, v188
	v_fmac_f32_e32 v199, v151, v189
	v_fmac_f32_e32 v200, v151, v190
	v_fmac_f32_e32 v201, v151, v191
	v_fmac_f32_e32 v202, v151, v192
	v_fmac_f32_e32 v203, v151, v193
	v_fmac_f32_e32 v204, v151, v194
	v_fmac_f32_e32 v205, v151, v196
	v_fmac_f32_e32 v198, v150, v189
	v_fmac_f32_e32 v199, v150, v190
	v_fmac_f32_e32 v200, v150, v191
	v_fmac_f32_e32 v201, v150, v192
	v_fmac_f32_e32 v202, v150, v193
	v_fmac_f32_e32 v203, v150, v194
	v_fmac_f32_e32 v204, v150, v196
	v_fmac_f32_e32 v205, v150, v197
	ds_write_b32 v206, v198 offset:8704
	ds_write_b32 v206, v199 offset:8964
	ds_write_b32 v206, v200 offset:9224
	ds_write_b32 v206, v201 offset:9484
	ds_write_b32 v206, v202 offset:9744
	ds_write_b32 v206, v203 offset:10004
	ds_write_b32 v206, v204 offset:10264
	ds_write_b32 v206, v205 offset:10524
	v_cvt_pk_bf16_f32 v186, v198, v1
	v_cvt_pk_bf16_f32 v187, v199, v1
	ds_write_b16 v207, v186 offset:25344
	v_cvt_pk_bf16_f32 v188, v200, v1
	ds_write_b16 v207, v187 offset:25488
	v_cvt_pk_bf16_f32 v189, v201, v1
	ds_write_b16 v207, v188 offset:25632
	v_cvt_pk_bf16_f32 v190, v202, v1
	ds_write_b16 v207, v189 offset:25776
	v_cvt_pk_bf16_f32 v191, v203, v1
	ds_write_b16 v207, v190 offset:25920
	v_cvt_pk_bf16_f32 v192, v204, v1
	ds_write_b16 v207, v191 offset:26064
	v_cvt_pk_bf16_f32 v193, v205, v1
	ds_write_b16 v207, v192 offset:26208
	ds_write_b16 v207, v193 offset:26352
	s_waitcnt lgkmcnt(0)
	s_barrier
	ds_read_b32 v186, v147 offset:8704
	ds_read_b32 v187, v147 offset:8964
	ds_read_b32 v188, v147 offset:9224
	ds_read_b32 v189, v147 offset:9484
	ds_read_b32 v190, v147 offset:8768
	ds_read_b32 v191, v147 offset:9028
	ds_read_b32 v192, v147 offset:9288
	ds_read_b32 v193, v147 offset:9548
	ds_read_b32 v194, v147 offset:8832
	ds_read_b32 v196, v147 offset:9092
	ds_read_b32 v197, v147 offset:9352
	ds_read_b32 v198, v147 offset:9612
	ds_read_b32 v199, v147 offset:8896
	ds_read_b32 v200, v147 offset:9156
	ds_read_b32 v201, v147 offset:9416
	ds_read_b32 v202, v147 offset:9676
	ds_read_b128 v[14:17], v44 offset:25344
	ds_read_b128 v[10:13], v44 offset:25408
	ds_read_b128 v[32:35], v67 offset:34560
	ds_read_b128 v[154:157], v67 offset:34624
	s_waitcnt lgkmcnt(1)
	v_mfma_f32_16x16x32_bf16 v[32:35], v[14:17], v[32:35], 0
	ds_read_b128 v[158:161], v68 offset:43840
	s_waitcnt lgkmcnt(1)
	v_mfma_f32_16x16x32_bf16 v[32:35], v[10:13], v[154:157], v[32:35]
	ds_read_b128 v[154:157], v68 offset:43776
	s_waitcnt lgkmcnt(0)
	v_mfma_f32_16x16x32_bf16 v[154:157], v[14:17], v[154:157], 0
	s_waitcnt vmcnt(7)
	s_nop 3
	v_fmamk_f32 v0, v32, 0xbfb8aa3b, v22
	v_exp_f32_e32 v0, v0
	v_mfma_f32_16x16x32_bf16 v[154:157], v[10:13], v[158:161], v[154:157]
	v_fmamk_f32 v33, v33, 0xbfb8aa3b, v22
	v_add_f32_e32 v0, 1.0, v0
	v_rcp_f32_e32 v0, v0
	v_exp_f32_e32 v33, v33
	s_waitcnt vmcnt(3)
	s_nop 2
	v_fmamk_f32 v32, v154, 0xbfb8aa3b, v38
	v_mul_f32_e32 v0, v19, v0
	v_exp_f32_e32 v0, v0
	v_exp_f32_e32 v32, v32
	v_add_f32_e32 v33, 1.0, v33
	v_rcp_f32_e32 v33, v33
	v_fma_f32 v37, -v0, v0, 1.0
	v_max_f32_e32 v37, 0, v37
	ds_write_b32 v69, v0
	v_add_f32_e32 v32, 1.0, v32
	v_sqrt_f32_e32 v41, v37
	v_rcp_f32_e32 v32, v32
	v_fmamk_f32 v34, v34, 0xbfb8aa3b, v22
	v_mov_b32_e32 v0, v41
	v_exp_f32_e32 v34, v34
	v_mul_f32_e32 v0, v32, v0
	s_waitcnt lgkmcnt(0)
	v_mul_f32_e32 v0, v186, v0
	ds_write_b32 v70, v0
	v_mul_f32_e32 v0, v19, v33
	v_exp_f32_e32 v0, v0
	v_fmamk_f32 v32, v155, 0xbfb8aa3b, v38
	v_exp_f32_e32 v32, v32
	v_fma_f32 v33, -v0, v0, 1.0
	v_max_f32_e32 v33, 0, v33
	ds_write_b32 v71, v0
	v_add_f32_e32 v32, 1.0, v32
	v_sqrt_f32_e32 v37, v33
	v_rcp_f32_e32 v32, v32
	v_mov_b32_e32 v0, v37
	v_add_f32_e32 v33, 1.0, v34
	v_rcp_f32_e32 v33, v33
	v_mul_f32_e32 v0, v32, v0
	v_mul_f32_e32 v0, v187, v0
	ds_write_b32 v72, v0
	v_mul_f32_e32 v0, v19, v33
	v_exp_f32_e32 v0, v0
	v_fmamk_f32 v32, v156, 0xbfb8aa3b, v38
	v_exp_f32_e32 v32, v32
	v_fma_f32 v33, -v0, v0, 1.0
	v_max_f32_e32 v33, 0, v33
	ds_write_b32 v73, v0
	v_add_f32_e32 v32, 1.0, v32
	v_sqrt_f32_e32 v34, v33
	v_rcp_f32_e32 v32, v32
	v_mov_b32_e32 v0, v34
	v_fmamk_f32 v34, v35, 0xbfb8aa3b, v22
	v_exp_f32_e32 v34, v34
	s_nop 0
	v_add_f32_e32 v33, 1.0, v34
	v_rcp_f32_e32 v33, v33
	v_mul_f32_e32 v0, v32, v0
	v_mul_f32_e32 v0, v188, v0
	ds_write_b32 v74, v0
	v_mul_f32_e32 v0, v19, v33
	v_exp_f32_e32 v0, v0
	v_fmamk_f32 v32, v157, 0xbfb8aa3b, v38
	v_exp_f32_e32 v32, v32
	v_fma_f32 v33, -v0, v0, 1.0
	v_max_f32_e32 v33, 0, v33
	ds_write_b32 v75, v0
	v_add_f32_e32 v32, 1.0, v32
	v_sqrt_f32_e32 v34, v33
	v_rcp_f32_e32 v32, v32
	v_mov_b32_e32 v0, v34
	v_mul_f32_e32 v0, v32, v0
	v_mul_f32_e32 v0, v0, v189
	ds_write_b32 v76, v0
	ds_read_b128 v[32:35], v67 offset:36864
	ds_read_b128 v[154:157], v67 offset:36928
	s_waitcnt lgkmcnt(1)
; __device__ __forceinline__ float sigm(float x) { return __builtin_amdgcn_rcpf(1.0f + __expf(-x)); }
; template <int PASS>
; __device__ void lru_items(const Params& p, unsigned char* shm, int l) {
;     ...
;           for (int jt = 0; jt < 4; ++jt) {
;               f32x4 accr = (f32x4){0.f, 0.f, 0.f, 0.f}, acci = (f32x4){0.f, 0.f, 0.f, 0.f};
;               const bf16_t* wr_ = wt + ((d * 2 + 0) * 64 + jt * 16 + fr) * 72 + fq * 8; const bf16_t* wi_ = wt + ((d * 2 + 1) * 64 + jt * 16 + fr) * 72 + fq * 8;
;               accr = __builtin_amdgcn_mfma_f32_16x16x32_bf16(a0, *(const bf16x8*)wr_, accr, 0, 0, 0);
;               accr = __builtin_amdgcn_mfma_f32_16x16x32_bf16(a1, *(const bf16x8*)(wr_ + 32), accr, 0, 0, 0);
;               acci = __builtin_amdgcn_mfma_f32_16x16x32_bf16(a0, *(const bf16x8*)wi_, acci, 0, 0, 0);
;               acci = __builtin_amdgcn_mfma_f32_16x16x32_bf16(a1, *(const bf16x8*)(wi_ + 32), acci, 0, 0, 0);
;               const int j = jt * 16 + fr;
; #pragma unroll
;               for (int i = 0; i < 4; ++i) { const int t = tt * 16 + fq * 4 + i;
;                   const float r = sigm(accr[i] + gba[jt]), ig = sigm(acci[i] + gbx[jt]), a = __expf(r * gsp[jt]);
;                   As[(d * 64 + t) * 64 + j] = a;
;                   Bs[(d * 64 + t) * 64 + j] = sqrtf(fmaxf(1.0f - a * a, 0.f)) * ig * xcf[t * 65 + j]; }
;           } }
	v_mfma_f32_16x16x32_bf16 v[32:35], v[14:17], v[32:35], 0
	ds_read_b128 v[158:161], v68 offset:46144
	s_waitcnt lgkmcnt(1)
	v_mfma_f32_16x16x32_bf16 v[32:35], v[10:13], v[154:157], v[32:35]
	ds_read_b128 v[154:157], v68 offset:46080
	s_waitcnt lgkmcnt(0)
	v_mfma_f32_16x16x32_bf16 v[154:157], v[14:17], v[154:157], 0
	s_nop 4
	v_fmamk_f32 v0, v32, 0xbfb8aa3b, v23
	v_exp_f32_e32 v0, v0
	v_mfma_f32_16x16x32_bf16 v[154:157], v[10:13], v[158:161], v[154:157]
	v_fmamk_f32 v33, v33, 0xbfb8aa3b, v23
	v_add_f32_e32 v0, 1.0, v0
	v_rcp_f32_e32 v0, v0
	v_exp_f32_e32 v33, v33
	s_waitcnt vmcnt(2)
	s_nop 2
	v_fmamk_f32 v32, v154, 0xbfb8aa3b, v39
	v_mul_f32_e32 v0, v18, v0
	v_exp_f32_e32 v0, v0
	v_exp_f32_e32 v32, v32
	v_add_f32_e32 v33, 1.0, v33
	v_rcp_f32_e32 v33, v33
	v_fma_f32 v37, -v0, v0, 1.0
	v_max_f32_e32 v37, 0, v37
	ds_write_b32 v77, v0
	v_add_f32_e32 v32, 1.0, v32
	v_sqrt_f32_e32 v41, v37
	v_rcp_f32_e32 v32, v32
	v_fmamk_f32 v34, v34, 0xbfb8aa3b, v23
	v_mov_b32_e32 v0, v41
	v_exp_f32_e32 v34, v34
	v_mul_f32_e32 v0, v32, v0
	v_mul_f32_e32 v0, v190, v0
	ds_write_b32 v78, v0
	v_mul_f32_e32 v0, v18, v33
	v_exp_f32_e32 v0, v0
	v_fmamk_f32 v32, v155, 0xbfb8aa3b, v39
	v_exp_f32_e32 v32, v32
	v_fma_f32 v33, -v0, v0, 1.0
	v_max_f32_e32 v33, 0, v33
	ds_write_b32 v79, v0
	v_add_f32_e32 v32, 1.0, v32
	v_sqrt_f32_e32 v37, v33
	v_rcp_f32_e32 v32, v32
	v_mov_b32_e32 v0, v37
	v_add_f32_e32 v33, 1.0, v34
	v_rcp_f32_e32 v33, v33
	v_mul_f32_e32 v0, v32, v0
	v_mul_f32_e32 v0, v191, v0
	ds_write_b32 v80, v0
	v_mul_f32_e32 v0, v18, v33
	v_exp_f32_e32 v0, v0
	v_fmamk_f32 v32, v156, 0xbfb8aa3b, v39
	v_exp_f32_e32 v32, v32
	v_fma_f32 v33, -v0, v0, 1.0
	v_max_f32_e32 v33, 0, v33
	ds_write_b32 v81, v0
	v_add_f32_e32 v32, 1.0, v32
	v_sqrt_f32_e32 v34, v33
	v_rcp_f32_e32 v32, v32
	v_mov_b32_e32 v0, v34
	v_fmamk_f32 v34, v35, 0xbfb8aa3b, v23
	v_exp_f32_e32 v34, v34
	s_nop 0
	v_add_f32_e32 v33, 1.0, v34
	v_rcp_f32_e32 v33, v33
	v_mul_f32_e32 v0, v32, v0
	v_mul_f32_e32 v0, v192, v0
	ds_write_b32 v82, v0
	v_mul_f32_e32 v0, v18, v33
	v_exp_f32_e32 v0, v0
	v_fmamk_f32 v32, v157, 0xbfb8aa3b, v39
	v_exp_f32_e32 v32, v32
	v_fma_f32 v33, -v0, v0, 1.0
	v_max_f32_e32 v33, 0, v33
	ds_write_b32 v83, v0
	v_add_f32_e32 v32, 1.0, v32
	v_sqrt_f32_e32 v34, v33
	v_rcp_f32_e32 v32, v32
	v_mov_b32_e32 v0, v34
	v_mul_f32_e32 v0, v32, v0
	v_mul_f32_e32 v0, v0, v193
	ds_write_b32 v84, v0
	ds_read_b128 v[32:35], v67 offset:39168
	ds_read_b128 v[154:157], v67 offset:39232
	s_waitcnt lgkmcnt(1)
	v_mfma_f32_16x16x32_bf16 v[32:35], v[14:17], v[32:35], 0
	ds_read_b128 v[158:161], v68 offset:48448
	s_waitcnt lgkmcnt(1)
	v_mfma_f32_16x16x32_bf16 v[32:35], v[10:13], v[154:157], v[32:35]
	ds_read_b128 v[154:157], v68 offset:48384
	s_waitcnt lgkmcnt(0)
	v_mfma_f32_16x16x32_bf16 v[154:157], v[14:17], v[154:157], 0
	s_nop 4
	v_fmamk_f32 v0, v32, 0xbfb8aa3b, v24
	v_exp_f32_e32 v0, v0
	v_mfma_f32_16x16x32_bf16 v[154:157], v[10:13], v[158:161], v[154:157]
	v_fmamk_f32 v33, v33, 0xbfb8aa3b, v24
	v_add_f32_e32 v0, 1.0, v0
	v_rcp_f32_e32 v0, v0
	v_exp_f32_e32 v33, v33
	s_waitcnt vmcnt(1)
	s_nop 2
	v_fmamk_f32 v32, v154, 0xbfb8aa3b, v40
	v_mul_f32_e32 v0, v21, v0
	v_exp_f32_e32 v0, v0
	v_exp_f32_e32 v32, v32
	v_add_f32_e32 v33, 1.0, v33
	v_rcp_f32_e32 v33, v33
	v_fma_f32 v37, -v0, v0, 1.0
	v_max_f32_e32 v37, 0, v37
	ds_write_b32 v85, v0
	v_add_f32_e32 v32, 1.0, v32
	v_sqrt_f32_e32 v41, v37
	v_rcp_f32_e32 v32, v32
	v_fmamk_f32 v34, v34, 0xbfb8aa3b, v24
	v_mov_b32_e32 v0, v41
	v_exp_f32_e32 v34, v34
	v_mul_f32_e32 v0, v32, v0
	v_mul_f32_e32 v0, v194, v0
	ds_write_b32 v86, v0
	v_mul_f32_e32 v0, v21, v33
	v_exp_f32_e32 v0, v0
	v_fmamk_f32 v32, v155, 0xbfb8aa3b, v40
	v_exp_f32_e32 v32, v32
	v_fma_f32 v33, -v0, v0, 1.0
	v_max_f32_e32 v33, 0, v33
	ds_write_b32 v87, v0
	v_add_f32_e32 v32, 1.0, v32
	v_sqrt_f32_e32 v37, v33
	v_rcp_f32_e32 v32, v32
	v_mov_b32_e32 v0, v37
	v_add_f32_e32 v33, 1.0, v34
	v_rcp_f32_e32 v33, v33
	v_mul_f32_e32 v0, v32, v0
	v_mul_f32_e32 v0, v196, v0
	ds_write_b32 v88, v0
	v_mul_f32_e32 v0, v21, v33
	v_exp_f32_e32 v0, v0
	v_fmamk_f32 v32, v156, 0xbfb8aa3b, v40
	v_exp_f32_e32 v32, v32
	v_fma_f32 v33, -v0, v0, 1.0
	v_max_f32_e32 v33, 0, v33
	ds_write_b32 v89, v0
	v_add_f32_e32 v32, 1.0, v32
	v_sqrt_f32_e32 v34, v33
	v_rcp_f32_e32 v32, v32
	v_mov_b32_e32 v0, v34
	v_fmamk_f32 v34, v35, 0xbfb8aa3b, v24
	v_exp_f32_e32 v34, v34
	s_nop 0
	v_add_f32_e32 v33, 1.0, v34
	v_rcp_f32_e32 v33, v33
	v_mul_f32_e32 v0, v32, v0
	v_mul_f32_e32 v0, v197, v0
	ds_write_b32 v90, v0
	v_mul_f32_e32 v0, v21, v33
	v_exp_f32_e32 v0, v0
	v_fmamk_f32 v32, v157, 0xbfb8aa3b, v40
	v_exp_f32_e32 v32, v32
	v_fma_f32 v33, -v0, v0, 1.0
	v_max_f32_e32 v33, 0, v33
	ds_write_b32 v91, v0
	v_add_f32_e32 v32, 1.0, v32
	v_sqrt_f32_e32 v34, v33
	v_rcp_f32_e32 v32, v32
	v_mov_b32_e32 v0, v34
	v_mul_f32_e32 v0, v32, v0
	v_mul_f32_e32 v0, v0, v198
	ds_write_b32 v92, v0
	ds_read_b128 v[32:35], v67 offset:41472
	ds_read_b128 v[154:157], v67 offset:41536
	s_waitcnt lgkmcnt(1)
	v_mfma_f32_16x16x32_bf16 v[32:35], v[14:17], v[32:35], 0
	ds_read_b128 v[158:161], v68 offset:50752
	s_waitcnt lgkmcnt(1)
	v_mfma_f32_16x16x32_bf16 v[32:35], v[10:13], v[154:157], v[32:35]
	ds_read_b128 v[154:157], v68 offset:50688
	s_waitcnt lgkmcnt(0)
; __device__ __forceinline__ float sigm(float x) { return __builtin_amdgcn_rcpf(1.0f + __expf(-x)); }
; template <int PASS>
; __device__ void lru_items(const Params& p, unsigned char* shm, int l) {
;     ...
;           for (int jt = 0; jt < 4; ++jt) {
;               f32x4 accr = (f32x4){0.f, 0.f, 0.f, 0.f}, acci = (f32x4){0.f, 0.f, 0.f, 0.f};
;               const bf16_t* wr_ = wt + ((d * 2 + 0) * 64 + jt * 16 + fr) * 72 + fq * 8; const bf16_t* wi_ = wt + ((d * 2 + 1) * 64 + jt * 16 + fr) * 72 + fq * 8;
;               accr = __builtin_amdgcn_mfma_f32_16x16x32_bf16(a0, *(const bf16x8*)wr_, accr, 0, 0, 0);
;               accr = __builtin_amdgcn_mfma_f32_16x16x32_bf16(a1, *(const bf16x8*)(wr_ + 32), accr, 0, 0, 0);
;               acci = __builtin_amdgcn_mfma_f32_16x16x32_bf16(a0, *(const bf16x8*)wi_, acci, 0, 0, 0);
;               acci = __builtin_amdgcn_mfma_f32_16x16x32_bf16(a1, *(const bf16x8*)(wi_ + 32), acci, 0, 0, 0);
;               const int j = jt * 16 + fr;
; #pragma unroll
;               for (int i = 0; i < 4; ++i) { const int t = tt * 16 + fq * 4 + i;
;                   const float r = sigm(accr[i] + gba[jt]), ig = sigm(acci[i] + gbx[jt]), a = __expf(r * gsp[jt]);
;                   As[(d * 64 + t) * 64 + j] = a;
;                   Bs[(d * 64 + t) * 64 + j] = sqrtf(fmaxf(1.0f - a * a, 0.f)) * ig * xcf[t * 65 + j]; }
;           } }
;         __syncthreads();
;         {
;             const int seg = tid >> 7, d = (tid >> 6) & 1, j = tid & 63;
;             float h = 0.f, P = 1.f;
; #pragma unroll
;             for (int s = 0; s < 16; ++s) { const int st = seg * 16 + s, t = d ? 63 - st : st; const float a = As[(d * 64 + t) * 64 + j]; h = a * h + Bs[(d * 64 + t) * 64 + j]; P *= a; }
;             Pq[seg * 128 + (tid & 127)] = P; Hq[seg * 128 + (tid & 127)] = h;
;             __syncthreads();
;             if (PASS == 0) {
;                 if (tid < 128) { float hh = Hq[tid], PP = Pq[tid];
; #pragma unroll
;                     for (int q = 1; q < 4; ++q) { const float pq = Pq[q * 128 + tid]; hh = pq * hh + Hq[q * 128 + tid]; PP *= pq; }
;                     SA[so] = PP; SH[so] = hh; }
	v_mfma_f32_16x16x32_bf16 v[14:17], v[14:17], v[154:157], 0
	s_nop 4
	v_fmamk_f32 v0, v32, 0xbfb8aa3b, v25
	v_exp_f32_e32 v0, v0
	s_nop 0
	v_mfma_f32_16x16x32_bf16 v[10:13], v[10:13], v[158:161], v[14:17]
	v_add_f32_e32 v0, 1.0, v0
	v_rcp_f32_e32 v0, v0
	s_nop 0
	v_mul_f32_e32 v0, v20, v0
	v_exp_f32_e32 v0, v0
	s_waitcnt vmcnt(0)
	s_nop 1
	v_fmamk_f32 v10, v10, 0xbfb8aa3b, v36
	v_exp_f32_e32 v10, v10
	v_fma_f32 v14, -v0, v0, 1.0
	v_max_f32_e32 v14, 0, v14
	ds_write_b32 v93, v0
	v_add_f32_e32 v10, 1.0, v10
	v_sqrt_f32_e32 v15, v14
	v_rcp_f32_e32 v10, v10
	v_mov_b32_e32 v0, v15
	v_fmamk_f32 v15, v33, 0xbfb8aa3b, v25
	v_exp_f32_e32 v15, v15
	s_nop 0
	v_add_f32_e32 v14, 1.0, v15
	v_rcp_f32_e32 v14, v14
	v_mul_f32_e32 v0, v10, v0
	v_mul_f32_e32 v0, v199, v0
	ds_write_b32 v94, v0
	v_mul_f32_e32 v0, v20, v14
	v_exp_f32_e32 v0, v0
	v_fmamk_f32 v10, v11, 0xbfb8aa3b, v36
	v_exp_f32_e32 v10, v10
	v_fma_f32 v11, -v0, v0, 1.0
	v_max_f32_e32 v11, 0, v11
	ds_write_b32 v95, v0
	v_add_f32_e32 v10, 1.0, v10
	v_sqrt_f32_e32 v14, v11
	v_rcp_f32_e32 v10, v10
	v_mov_b32_e32 v0, v14
	v_fmamk_f32 v14, v34, 0xbfb8aa3b, v25
	v_exp_f32_e32 v14, v14
	s_nop 0
	v_add_f32_e32 v11, 1.0, v14
	v_rcp_f32_e32 v11, v11
	v_mul_f32_e32 v0, v10, v0
	v_mul_f32_e32 v0, v200, v0
	ds_write_b32 v96, v0
	v_mul_f32_e32 v0, v20, v11
	v_exp_f32_e32 v0, v0
	v_fmamk_f32 v10, v12, 0xbfb8aa3b, v36
	v_exp_f32_e32 v10, v10
	v_fma_f32 v11, -v0, v0, 1.0
	v_max_f32_e32 v11, 0, v11
	ds_write_b32 v97, v0
	v_add_f32_e32 v10, 1.0, v10
	v_sqrt_f32_e32 v12, v11
	v_rcp_f32_e32 v10, v10
	v_mov_b32_e32 v0, v12
	v_fmamk_f32 v12, v35, 0xbfb8aa3b, v25
	v_exp_f32_e32 v12, v12
	s_nop 0
	v_add_f32_e32 v11, 1.0, v12
	v_rcp_f32_e32 v11, v11
	v_mul_f32_e32 v0, v10, v0
	v_mul_f32_e32 v0, v201, v0
	ds_write_b32 v98, v0
	v_mul_f32_e32 v0, v20, v11
	v_exp_f32_e32 v0, v0
	v_fmamk_f32 v10, v13, 0xbfb8aa3b, v36
	v_exp_f32_e32 v10, v10
	v_fma_f32 v11, -v0, v0, 1.0
	v_max_f32_e32 v11, 0, v11
	ds_write_b32 v99, v0
	v_add_f32_e32 v10, 1.0, v10
	v_sqrt_f32_e32 v12, v11
	v_rcp_f32_e32 v10, v10
	v_mov_b32_e32 v0, v12
	v_mul_f32_e32 v0, v10, v0
	v_mul_f32_e32 v0, v0, v202
	ds_write_b32 v100, v0
	s_waitcnt lgkmcnt(0)
	s_barrier
	ds_read_b32 v183, v101
	ds_read_b32 v184, v102
	ds_read_b32 v185, v103
	ds_read_b32 v186, v104
	ds_read_b32 v187, v105
	ds_read_b32 v188, v106
	ds_read_b32 v189, v107
	ds_read_b32 v190, v108
	ds_read_b32 v191, v109
	ds_read_b32 v192, v110
	ds_read_b32 v193, v111
	ds_read_b32 v194, v112
	ds_read_b32 v196, v113
	ds_read_b32 v197, v114
	ds_read_b32 v198, v115
	ds_read_b32 v199, v116
	ds_read_b32 v200, v117
	ds_read_b32 v201, v118
	ds_read_b32 v202, v119
	ds_read_b32 v203, v120
	ds_read_b32 v204, v121
	ds_read_b32 v205, v122
	ds_read_b32 v206, v123
	ds_read_b32 v207, v124
	ds_read_b32 v208, v125
	ds_read_b32 v209, v126
	ds_read_b32 v210, v127
	ds_read_b32 v211, v128
	ds_read_b32 v212, v129
	ds_read_b32 v213, v131
	ds_read_b32 v214, v132
	ds_read_b32 v215, v133
	s_waitcnt lgkmcnt(0)
	v_fmac_f32_e32 v184, 0, v183
	v_fmac_f32_e32 v186, v184, v185
	v_mul_f32_e32 v183, v183, v185
	v_fmac_f32_e32 v188, v186, v187
	v_mul_f32_e32 v183, v183, v187
	v_fmac_f32_e32 v190, v188, v189
	v_mul_f32_e32 v183, v183, v189
	v_fmac_f32_e32 v192, v190, v191
	v_mul_f32_e32 v183, v183, v191
	v_fmac_f32_e32 v194, v192, v193
	v_mul_f32_e32 v183, v183, v193
	v_fmac_f32_e32 v197, v194, v196
	v_mul_f32_e32 v183, v183, v196
	v_fmac_f32_e32 v199, v197, v198
	v_mul_f32_e32 v183, v183, v198
	v_fmac_f32_e32 v201, v199, v200
	v_mul_f32_e32 v183, v183, v200
	v_fmac_f32_e32 v203, v201, v202
	v_mul_f32_e32 v183, v183, v202
	v_fmac_f32_e32 v205, v203, v204
	v_mul_f32_e32 v183, v183, v204
	v_fmac_f32_e32 v207, v205, v206
	v_mul_f32_e32 v183, v183, v206
	v_mul_f32_e32 v183, v183, v208
	v_fmac_f32_e32 v209, v207, v208
	v_mul_f32_e32 v183, v183, v210
	v_fmac_f32_e32 v211, v209, v210
	v_mul_f32_e32 v183, v183, v212
	v_fmac_f32_e32 v213, v211, v212
	v_mul_f32_e32 v183, v183, v214
	v_fmac_f32_e32 v215, v213, v214
	ds_write_b32 v45, v183
	ds_write_b32 v46, v215
	s_waitcnt lgkmcnt(0)
	s_barrier
	s_and_saveexec_b64 s[40:41], s[38:39]
	s_cbranch_execz .LBB0_295
	ds_read_b32 v0, v46
	ds_read_b32 v12, v45
	ds_read_b32 v13, v134
	ds_read_b32 v14, v135
	s_ashr_i32 s0, s2, 3
	v_and_or_b32 v10, s0, -2, v43
	v_ashrrev_i32_e32 v11, 31, v10
	s_mov_b32 s51, s49
	s_waitcnt lgkmcnt(0)
	v_fmac_f32_e32 v14, v0, v13
	v_mul_f32_e32 v0, v12, v13
	ds_read_b32 v12, v136
	ds_read_b32 v13, v137
	v_lshlrev_b64 v[10:11], 10, v[10:11]
	v_lshl_add_u64 v[10:11], v[10:11], 0, s[50:51]
	v_or_b32_e32 v10, v10, v26
	s_waitcnt lgkmcnt(1)
	v_mul_f32_e32 v0, v0, v12
	s_waitcnt lgkmcnt(0)
	v_fmac_f32_e32 v13, v14, v12
	ds_read_b32 v12, v138
	ds_read_b32 v14, v139
	v_lshlrev_b64 v[10:11], 2, v[10:11]
	s_movk_i32 s23, 0xff7f
	v_readlane_b32 s22, v254, 8
	s_movk_i32 s17, 0x84
	s_mov_b32 s15, 0xfe03f81
	s_movk_i32 s10, 0xc00
	s_waitcnt lgkmcnt(0)
	v_fmac_f32_e32 v14, v13, v12
	v_mul_f32_e32 v0, v0, v12
	v_lshl_add_u64 v[12:13], s[34:35], 0, v[10:11]
	v_lshl_add_u64 v[10:11], s[96:97], 0, v[10:11]
	global_store_dword v[12:13], v0, off
	global_store_dword v[10:11], v14, off
	s_branch .LBB0_295
